# stack: bias as MFMA C operand (24 MFMAs per step) + per-XCD attention queues + scan step LDS de-serialisation + packed f32 ops split in the attention and scan loops
# speedup vs baseline: 1.0135x; 1.0049x over previous
.LBB0_363:
	v_cvt_pk_bf16_f32 v48, v16, v17
	v_cvt_pk_bf16_f32 v49, v18, v19
	v_cvt_pk_bf16_f32 v50, v20, v21
	v_cvt_pk_bf16_f32 v51, v22, v23
	global_load_dwordx4 v[128:131], v[214:215], off offset:-4096
	global_load_dwordx4 v[124:127], v[214:215], off
	ds_read2_b64 v[32:35], v229 offset1:2
	ds_read2_b64 v[64:67], v229 offset0:4 offset1:6
	v_add_u32_e32 v235, 0x4000, v229
	s_waitcnt lgkmcnt(1)
	v_mfma_f32_32x32x16_bf16 v[32:47], v[48:51], v[32:35], 0
	ds_read2_b64 v[52:55], v235 offset0:32 offset1:34
	v_cvt_pk_bf16_f32 v68, v24, v25
	v_cvt_pk_bf16_f32 v69, v26, v27
	v_cvt_pk_bf16_f32 v70, v28, v29
	v_cvt_pk_bf16_f32 v71, v30, v31
	v_add_u32_e32 v236, s17, v219
	v_add_u32_e32 v237, 0x2080, v220
	s_waitcnt lgkmcnt(0)
	v_mfma_f32_32x32x16_bf16 v[48:63], v[48:51], v[52:55], 0
	v_add_u32_e32 v242, 0x20c8, v220
	v_add_u32_e32 v243, 0x20e0, v220
	v_add_u32_e32 v244, 0x20e8, v220
	v_mov_b32_e32 v175, v174
	v_mul_f32_e64 v30, v174, v30
	v_mul_f32_e64 v31, v175, v31
	v_mul_f32_e32 v28, v174, v28
	v_mul_f32_e32 v29, v175, v29
	v_mul_f32_e32 v26, v174, v26
	v_mul_f32_e32 v27, v175, v27
	v_mfma_f32_32x32x16_bf16 v[32:47], v[68:71], v[64:67], v[32:47]
	ds_read2_b64 v[64:67], v235 offset0:36 offset1:38
	v_mul_f32_e64 v24, v174, v24
	v_mul_f32_e64 v25, v175, v25
	v_mul_f32_e64 v22, v174, v22
	v_mul_f32_e64 v23, v175, v23
	v_mul_f32_e32 v20, v174, v20
	v_mul_f32_e32 v21, v175, v21
	v_mul_f32_e32 v18, v174, v18
	v_mul_f32_e32 v19, v175, v19
	v_mul_f32_e32 v16, v210, v16
	v_mul_f32_e32 v17, v211, v17
	s_add_i32 s44, s0, 2
	s_waitcnt lgkmcnt(0)
	v_mfma_f32_32x32x16_bf16 v[48:63], v[68:71], v[64:67], v[48:63]
	v_cvt_pk_bf16_f32 v64, v0, v1
	v_cvt_pk_bf16_f32 v65, v2, v3
	v_cvt_pk_bf16_f32 v66, v4, v5
	v_cvt_pk_bf16_f32 v67, v6, v7
	ds_read2_b64 v[68:71], v229 offset0:8 offset1:10
	v_mul_f32_e32 v6, v174, v6
	v_mul_f32_e32 v7, v175, v7
	v_mul_f32_e32 v4, v174, v4
	v_mul_f32_e32 v5, v175, v5
	s_waitcnt lgkmcnt(0)
	v_mfma_f32_32x32x16_bf16 v[32:47], v[64:67], v[68:71], v[32:47]
	ds_read2_b64 v[68:71], v235 offset0:40 offset1:42
	v_mul_f32_e64 v2, v174, v2
	v_mul_f32_e64 v3, v175, v3
	v_mul_f32_e64 v0, v210, v0
	v_mul_f32_e64 v1, v211, v1
	s_min_u32 s1, s44, 61
	s_mul_i32 s1, s1, 0xc0000
	s_add_i32 s4, s1, 0x180000
	s_add_i32 s0, s0, 3
	s_waitcnt lgkmcnt(0)
	v_mfma_f32_32x32x16_bf16 v[48:63], v[64:67], v[68:71], v[48:63]
	v_cvt_pk_bf16_f32 v64, v8, v9
	v_cvt_pk_bf16_f32 v65, v10, v11
	v_cvt_pk_bf16_f32 v66, v12, v13
	v_cvt_pk_bf16_f32 v67, v14, v15
	ds_read2_b64 v[68:71], v229 offset0:12 offset1:14
	v_mul_f32_e32 v14, v174, v14
	v_mul_f32_e32 v15, v175, v15
	v_mul_f32_e32 v12, v174, v12
	v_mul_f32_e32 v13, v175, v13
	s_waitcnt lgkmcnt(0)
	v_mfma_f32_32x32x16_bf16 v[32:47], v[64:67], v[68:71], v[32:47]
	ds_read2_b64 v[68:71], v235 offset0:44 offset1:46
	ds_read_b64_tr_b16 v[132:133], v219
	ds_read_b64_tr_b16 v[134:135], v219 offset:768
	ds_read_b64_tr_b16 v[136:137], v219 offset:3072
	ds_read_b64_tr_b16 v[138:139], v219 offset:3840
	ds_read_b64_tr_b16 v[140:141], v219 offset:6144
	ds_read_b64_tr_b16 v[142:143], v219 offset:6912
	ds_read_b64_tr_b16 v[144:145], v219 offset:9216
	ds_read_b64_tr_b16 v[146:147], v219 offset:9984
	ds_read_b64_tr_b16 v[238:239], v236
	ds_read_b64_tr_b16 v[240:241], v236 offset:768
	v_mul_f32_e32 v10, v174, v10
	v_mul_f32_e32 v11, v175, v11
	v_mul_f32_e32 v8, v174, v8
	v_mul_f32_e32 v9, v175, v9
	s_min_u32 s1, s0, 62
	s_min_u32 s0, s0, 61
	s_waitcnt lgkmcnt(10)
	v_mfma_f32_32x32x16_bf16 v[48:63], v[64:67], v[68:71], v[48:63]
	v_mul_f32_e64 v78, v194, v46
	v_mul_f32_e64 v79, v195, v47
	v_mul_f32_e64 v76, v192, v44
	v_mul_f32_e64 v77, v193, v45
	v_mul_f32_e64 v74, v190, v42
	v_mul_f32_e64 v75, v191, v43
	v_mul_f32_e32 v72, v188, v40
	v_mul_f32_e32 v73, v189, v41
	v_mul_f32_e32 v70, v186, v38
	v_mul_f32_e32 v71, v187, v39
	v_mul_f32_e32 v68, v184, v36
	v_mul_f32_e32 v69, v185, v37
	v_mul_f32_e32 v66, v182, v34
	v_mul_f32_e32 v67, v183, v35
	v_mul_f32_e32 v64, v172, v32
	v_mul_f32_e32 v65, v173, v33
	s_nop 0
	v_mul_f32_e32 v46, v208, v62
	v_mul_f32_e32 v47, v209, v63
	v_mul_f32_e32 v44, v206, v60
	v_mul_f32_e32 v45, v207, v61
	v_mul_f32_e32 v42, v204, v58
	v_mul_f32_e32 v43, v205, v59
	v_mul_f32_e32 v40, v202, v56
	v_mul_f32_e32 v41, v203, v57
	v_mul_f32_e32 v38, v200, v54
	v_mul_f32_e32 v39, v201, v55
	v_mul_f32_e32 v36, v198, v52
	v_mul_f32_e32 v37, v199, v53
	v_mul_f32_e32 v34, v196, v50
	v_mul_f32_e32 v35, v197, v51
	v_mul_f32_e32 v32, v180, v48
	v_mul_f32_e32 v33, v181, v49
	s_waitcnt vmcnt(12) lgkmcnt(0)
	v_mfma_f32_32x32x16_bf16 v[64:79], v[238:241], v[84:87], v[64:79]
	s_nop 11
	ds_write2_b32 v220, v64, v65 offset1:1
	ds_write2_b32 v220, v66, v67 offset0:2 offset1:3
	ds_write2_b32 v220, v68, v69 offset0:8 offset1:9
	ds_write2_b32 v220, v70, v71 offset0:10 offset1:11
	ds_write2_b32 v220, v72, v73 offset0:16 offset1:17
	ds_write2_b32 v220, v74, v75 offset0:18 offset1:19
	ds_write2_b32 v220, v76, v77 offset0:24 offset1:25
	ds_write2_b32 v220, v78, v79 offset0:26 offset1:27
	s_waitcnt vmcnt(11)
	v_mfma_f32_32x32x16_bf16 v[32:47], v[238:241], v[80:83], v[32:47]
	v_add_u32_e32 v238, 0x2088, v220
	v_add_u32_e32 v239, 0x20a0, v220
	v_add_u32_e32 v240, 0x20a8, v220
	v_add_u32_e32 v241, 0x20c0, v220
	s_mul_i32 s0, s0, 0xc0000
	v_lshl_add_u64 v[214:215], v[214:215], 0, s[12:13]
	s_nop 5
	ds_write2_b32 v237, v32, v33 offset1:1
	ds_write2_b32 v238, v34, v35 offset1:1
	ds_write2_b32 v239, v36, v37 offset1:1
	ds_write2_b32 v240, v38, v39 offset1:1
	ds_write2_b32 v241, v40, v41 offset1:1
	ds_write2_b32 v242, v42, v43 offset1:1
	ds_write2_b32 v243, v44, v45 offset1:1
	ds_write2_b32 v244, v46, v47 offset1:1
	ds_read_b64_tr_b16 v[32:33], v230 offset:33280
	ds_read_b64_tr_b16 v[34:35], v230 offset:35584
	ds_read_b64_tr_b16 v[36:37], v230 offset:42496
	ds_read_b64_tr_b16 v[38:39], v230 offset:44800
	ds_read_b64_tr_b16 v[40:41], v230 offset:51712
	ds_read_b64_tr_b16 v[42:43], v230 offset:54016
	ds_read_b64_tr_b16 v[44:45], v230 offset:60928
	ds_read_b64_tr_b16 v[46:47], v230 offset:63232
	ds_read_b64_tr_b16 v[48:49], v230 offset:33344
	ds_read_b64_tr_b16 v[50:51], v230 offset:35648
	ds_read_b64_tr_b16 v[52:53], v230 offset:42560
	ds_read_b64_tr_b16 v[54:55], v230 offset:44864
	ds_read_b64_tr_b16 v[56:57], v230 offset:51776
	ds_read_b64_tr_b16 v[58:59], v230 offset:54080
	ds_read_b64_tr_b16 v[60:61], v230 offset:60992
	ds_read_b64_tr_b16 v[62:63], v230 offset:63296
	s_waitcnt lgkmcnt(14)
	v_mfma_f32_32x32x16_bf16 v[16:31], v[32:35], v[132:135], v[16:31]
	s_waitcnt lgkmcnt(12)
	v_mfma_f32_32x32x16_bf16 v[16:31], v[36:39], v[136:139], v[16:31]
	s_waitcnt lgkmcnt(10)
	v_mfma_f32_32x32x16_bf16 v[16:31], v[40:43], v[140:143], v[16:31]
	s_waitcnt lgkmcnt(8)
	v_mfma_f32_32x32x16_bf16 v[16:31], v[44:47], v[144:147], v[16:31]
	s_waitcnt lgkmcnt(6)
	v_mfma_f32_32x32x16_bf16 v[0:15], v[48:51], v[132:135], v[0:15]
	v_add_u32_e32 v134, 0x4100, v223
	v_add_u32_e32 v135, 0x8200, v223
	v_lshl_add_u64 v[132:133], v[212:213], 0, s[14:15]
	s_waitcnt lgkmcnt(4)
	v_mfma_f32_32x32x16_bf16 v[0:15], v[52:55], v[136:139], v[0:15]
	v_add_u32_e32 v137, 0x4108, v223
	v_add_u32_e32 v136, 0xc300, v223
	v_add_u32_e32 v138, 0x8208, v223
	v_add_u32_e32 v139, 0xc308, v223
	s_waitcnt lgkmcnt(2)
	v_mfma_f32_32x32x16_bf16 v[0:15], v[56:59], v[140:143], v[0:15]
	s_waitcnt lgkmcnt(0)
	s_barrier
	v_add_u32_e32 v140, 0x4110, v223
	v_add_u32_e32 v143, 0x4118, v223
	v_add_u32_e32 v141, 0x8210, v223
	v_mfma_f32_32x32x16_bf16 v[0:15], v[60:63], v[144:147], v[0:15]
	v_add_u32_e32 v146, v154, v217
	v_add_u32_e32 v147, 0x2080, v146
	v_add_u32_e32 v245, 0x4100, v146
	v_lshl_add_u64 v[32:33], v[170:171], 0, s[4:5]
	s_waitcnt vmcnt(10)
	ds_write2_b64 v146, v[88:89], v[90:91] offset1:1
	s_waitcnt vmcnt(9)
	ds_write_b128 v231, v[92:95] offset:33280
	s_waitcnt vmcnt(8)
	ds_write2_b64 v147, v[96:97], v[98:99] offset1:1
	s_waitcnt vmcnt(7)
	ds_write_b128 v231, v[100:103] offset:42496
	s_waitcnt vmcnt(6)
	ds_write2_b64 v245, v[104:105], v[106:107] offset1:1
	s_waitcnt vmcnt(5)
	ds_write_b128 v231, v[108:111] offset:51712
	v_add_u32_e32 v108, 0x6180, v146
	v_add_co_u32_e32 v34, vcc, s21, v32
	s_waitcnt vmcnt(4)
	ds_write2_b64 v108, v[112:113], v[114:115] offset1:1
	s_waitcnt vmcnt(3)
	ds_write_b128 v231, v[116:119] offset:60928
	s_waitcnt vmcnt(2)
	ds_write_b128 v234, v[120:123]
	v_addc_co_u32_e32 v35, vcc, 0, v33, vcc
	global_load_dwordx4 v[64:67], v[32:33], off
	global_load_dwordx4 v[68:71], v[32:33], off offset:2048
	global_load_dwordx4 v[72:75], v[34:35], off
	global_load_dwordx4 v[76:79], v[34:35], off offset:2048
	v_add_co_u32_e32 v34, vcc, s24, v32
	v_add_u32_e32 v142, 0xc310, v223
	s_nop 0
	v_addc_co_u32_e32 v35, vcc, 0, v33, vcc
	v_add_co_u32_e32 v32, vcc, s25, v32
	global_load_dwordx4 v[88:91], v[34:35], off
	global_load_dwordx4 v[92:95], v[34:35], off offset:2048
	v_addc_co_u32_e32 v33, vcc, 0, v33, vcc
	global_load_dwordx4 v[96:99], v[32:33], off
	global_load_dwordx4 v[100:103], v[32:33], off offset:2048
	v_lshl_add_u64 v[32:33], v[176:177], 0, s[4:5]
	global_load_dwordx4 v[104:107], v[32:33], off
	v_add_u32_e32 v144, 0x8218, v223
	v_add_u32_e32 v145, 0xc318, v223
	s_waitcnt lgkmcnt(3)
	ds_read2_b32 v[32:33], v223 offset1:1
	ds_read2_b32 v[34:35], v134 offset1:1
	ds_read2_b32 v[36:37], v135 offset1:1
	ds_read2_b32 v[38:39], v136 offset1:1
	ds_read2_b32 v[40:41], v224 offset1:1
	ds_read2_b32 v[42:43], v137 offset1:1
	ds_read2_b32 v[44:45], v138 offset1:1
	ds_read2_b32 v[46:47], v139 offset1:1
	s_lshl_b32 s4, s1, 13
	v_cvt_pk_bf16_f32 v114, v24, v25
	v_cvt_pk_bf16_f32 v115, v26, v27
	v_cvt_pk_bf16_f32 v116, v28, v29
	v_cvt_pk_bf16_f32 v117, v30, v31
	v_mul_f32_e32 v30, v174, v30
	v_mul_f32_e32 v31, v175, v31
	v_mul_f32_e32 v28, v174, v28
	v_mul_f32_e32 v29, v175, v29
	v_mul_f32_e32 v26, v174, v26
	v_mul_f32_e32 v27, v175, v27
	v_mul_f32_e32 v24, v174, v24
	v_mul_f32_e32 v25, v175, v25
	s_waitcnt lgkmcnt(4)
	ds_read2_b32 v[48:49], v225 offset1:1
	ds_read2_b32 v[50:51], v140 offset1:1
	ds_read2_b32 v[52:53], v141 offset1:1
	ds_read2_b32 v[54:55], v142 offset1:1
	v_add_f32_e32 v32, 0, v32
	v_add_f32_e32 v33, 0, v33
	s_nop 0
	v_add_f32_e32 v32, v32, v34
	v_add_f32_e32 v33, v33, v35
	s_nop 0
	v_add_f32_e32 v32, v32, v36
	v_add_f32_e32 v33, v33, v37
	s_nop 0
	v_add_f32_e32 v32, v32, v38
	v_add_f32_e32 v33, v33, v39
	s_nop 0
	v_cvt_pk_bf16_f32 v32, v32, v33
	s_waitcnt lgkmcnt(4)
	ds_read2_b32 v[56:57], v226 offset1:1
	ds_read2_b32 v[58:59], v143 offset1:1
	ds_read2_b32 v[60:61], v144 offset1:1
	ds_read2_b32 v[62:63], v145 offset1:1
	v_add_f32_e32 v40, 0, v40
	v_add_f32_e32 v41, 0, v41
	s_nop 0
	v_add_f32_e32 v40, v40, v42
	v_add_f32_e32 v41, v41, v43
	s_nop 0
	v_add_f32_e32 v40, v40, v44
	v_add_f32_e32 v41, v41, v45
	s_nop 0
	v_add_f32_e32 v40, v40, v46
	v_add_f32_e32 v41, v41, v47
	s_nop 0
	v_cvt_pk_bf16_f32 v33, v40, v41
	v_add_co_u32_e32 v36, vcc, s27, v132
	s_nop 1
	v_addc_co_u32_e32 v37, vcc, 0, v133, vcc
	s_waitcnt lgkmcnt(4)
	v_add_f32_e32 v48, 0, v48
	v_add_f32_e32 v49, 0, v49
	s_nop 0
	v_add_f32_e32 v48, v48, v50
	v_add_f32_e32 v49, v49, v51
	s_nop 0
	v_add_f32_e32 v48, v48, v52
	v_add_f32_e32 v49, v49, v53
	s_nop 0
	v_add_f32_e32 v48, v48, v54
	v_add_f32_e32 v49, v49, v55
	s_nop 0
	v_cvt_pk_bf16_f32 v34, v48, v49
	s_waitcnt lgkmcnt(0)
	v_add_f32_e32 v56, 0, v56
	v_add_f32_e32 v57, 0, v57
	s_nop 0
	v_add_f32_e32 v56, v56, v58
	v_add_f32_e32 v57, v57, v59
	s_nop 0
	v_add_f32_e32 v56, v56, v60
	v_add_f32_e32 v57, v57, v61
	s_nop 0
	v_add_f32_e32 v56, v56, v62
	v_add_f32_e32 v57, v57, v63
	s_nop 0
	v_cvt_pk_bf16_f32 v35, v56, v57
	global_store_dwordx4 v[36:37], v[32:35], off
	s_barrier
	s_nop 0
	v_lshl_add_u64 v[32:33], v[178:179], 0, s[4:5]
	v_add_co_u32_e32 v32, vcc, s16, v32
	s_nop 1
	v_addc_co_u32_e32 v33, vcc, 0, v33, vcc
	global_load_dwordx4 v[84:87], v[32:33], off offset:-4096
	global_load_dwordx4 v[80:83], v[32:33], off
	v_cvt_pk_bf16_f32 v32, v16, v17
	v_cvt_pk_bf16_f32 v33, v18, v19
	v_cvt_pk_bf16_f32 v34, v20, v21
	v_cvt_pk_bf16_f32 v35, v22, v23
	ds_read2_b64 v[36:39], v229 offset1:2
	ds_read2_b64 v[110:113], v229 offset0:4 offset1:6
	s_waitcnt lgkmcnt(1)
	v_mfma_f32_32x32x16_bf16 v[48:63], v[32:35], v[36:39], 0
	ds_read2_b64 v[36:39], v235 offset0:32 offset1:34
	v_mul_f32_e64 v22, v174, v22
	v_mul_f32_e64 v23, v175, v23
	v_mul_f32_e64 v20, v174, v20
	v_mul_f32_e64 v21, v175, v21
	v_mul_f32_e32 v18, v174, v18
	v_mul_f32_e32 v19, v175, v19
	v_mul_f32_e32 v16, v210, v16
	v_mul_f32_e32 v17, v211, v17
	s_add_i32 s4, s0, 0x180000
	s_add_u32 s14, s14, 0x180000
	s_waitcnt lgkmcnt(0)
	v_mfma_f32_32x32x16_bf16 v[32:47], v[32:35], v[36:39], 0
	s_addc_u32 s15, s15, 0
	s_cmp_gt_u32 s44, 61
	s_mov_b32 s0, s44
	v_mfma_f32_32x32x16_bf16 v[48:63], v[114:117], v[110:113], v[48:63]
	ds_read2_b64 v[110:113], v235 offset0:36 offset1:38
	s_waitcnt lgkmcnt(0)
	v_mfma_f32_32x32x16_bf16 v[32:47], v[114:117], v[110:113], v[32:47]
	v_cvt_pk_bf16_f32 v110, v0, v1
	v_cvt_pk_bf16_f32 v111, v2, v3
	v_cvt_pk_bf16_f32 v112, v4, v5
	v_cvt_pk_bf16_f32 v113, v6, v7
	ds_read2_b64 v[114:117], v229 offset0:8 offset1:10
	v_mul_f32_e32 v6, v174, v6
	v_mul_f32_e32 v7, v175, v7
	v_mul_f32_e32 v4, v174, v4
	v_mul_f32_e32 v5, v175, v5
	s_waitcnt lgkmcnt(0)
	v_mfma_f32_32x32x16_bf16 v[48:63], v[110:113], v[114:117], v[48:63]
	ds_read2_b64 v[114:117], v235 offset0:40 offset1:42
	v_mul_f32_e64 v2, v174, v2
	v_mul_f32_e64 v3, v175, v3
	v_mul_f32_e64 v0, v210, v0
	v_mul_f32_e64 v1, v211, v1
	s_waitcnt lgkmcnt(0)
	v_mfma_f32_32x32x16_bf16 v[32:47], v[110:113], v[114:117], v[32:47]
	v_cvt_pk_bf16_f32 v110, v8, v9
	v_cvt_pk_bf16_f32 v111, v10, v11
	v_cvt_pk_bf16_f32 v112, v12, v13
	v_cvt_pk_bf16_f32 v113, v14, v15
	ds_read2_b64 v[114:117], v229 offset0:12 offset1:14
	v_mul_f32_e32 v14, v174, v14
	v_mul_f32_e32 v15, v175, v15
	v_mul_f32_e32 v12, v174, v12
	v_mul_f32_e32 v13, v175, v13
	s_waitcnt lgkmcnt(0)
	v_mfma_f32_32x32x16_bf16 v[48:63], v[110:113], v[114:117], v[48:63]
	ds_read2_b64 v[114:117], v235 offset0:44 offset1:46
	v_mul_f32_e64 v10, v174, v10
	v_mul_f32_e64 v11, v175, v11
	v_mul_f32_e64 v8, v174, v8
	v_mul_f32_e64 v9, v175, v9
	s_nop 6
	v_mul_f32_e32 v62, v194, v62
	v_mul_f32_e32 v63, v195, v63
	s_waitcnt lgkmcnt(0)
	v_mfma_f32_32x32x16_bf16 v[32:47], v[110:113], v[114:117], v[32:47]
	ds_read_b64_tr_b16 v[110:111], v219
	ds_read_b64_tr_b16 v[112:113], v219 offset:768
	ds_read_b64_tr_b16 v[114:115], v219 offset:3072
	ds_read_b64_tr_b16 v[116:117], v219 offset:3840
	ds_read_b64_tr_b16 v[118:119], v219 offset:6144
	ds_read_b64_tr_b16 v[120:121], v219 offset:6912
	ds_read_b64_tr_b16 v[246:247], v219 offset:9216
	ds_read_b64_tr_b16 v[248:249], v219 offset:9984
	ds_read_b64_tr_b16 v[250:251], v236
	ds_read_b64_tr_b16 v[252:253], v236 offset:768
	v_mul_f32_e32 v60, v192, v60
	v_mul_f32_e32 v61, v193, v61
	v_mul_f32_e32 v58, v190, v58
	v_mul_f32_e32 v59, v191, v59
	v_mul_f32_e32 v56, v188, v56
	v_mul_f32_e32 v57, v189, v57
	v_mul_f32_e32 v54, v186, v54
	v_mul_f32_e32 v55, v187, v55
	v_mul_f32_e32 v52, v184, v52
	v_mul_f32_e32 v53, v185, v53
	v_mul_f32_e32 v50, v182, v50
	v_mul_f32_e32 v51, v183, v51
	v_mul_f32_e32 v48, v172, v48
	v_mul_f32_e32 v49, v173, v49
	v_mul_f32_e32 v46, v208, v46
	v_mul_f32_e32 v47, v209, v47
	v_mul_f32_e32 v44, v206, v44
	v_mul_f32_e32 v45, v207, v45
	s_waitcnt vmcnt(13) lgkmcnt(0)
	v_mfma_f32_32x32x16_bf16 v[48:63], v[250:253], v[128:131], v[48:63]
	v_mul_f32_e64 v42, v204, v42
	v_mul_f32_e64 v43, v205, v43
	v_mul_f32_e64 v40, v202, v40
	v_mul_f32_e64 v41, v203, v41
	v_mul_f32_e64 v38, v200, v38
	v_mul_f32_e64 v39, v201, v39
	v_mul_f32_e32 v36, v198, v36
	v_mul_f32_e32 v37, v199, v37
	v_mul_f32_e32 v34, v196, v34
	v_mul_f32_e32 v35, v197, v35
	v_mul_f32_e32 v32, v180, v32
	v_mul_f32_e32 v33, v181, v33
	s_waitcnt vmcnt(12)
	s_nop 0
	v_mfma_f32_32x32x16_bf16 v[32:47], v[250:253], v[124:127], v[32:47]
	ds_write2_b32 v220, v48, v49 offset1:1
	ds_write2_b32 v220, v50, v51 offset0:2 offset1:3
	ds_write2_b32 v220, v52, v53 offset0:8 offset1:9
	ds_write2_b32 v220, v54, v55 offset0:10 offset1:11
	ds_write2_b32 v220, v56, v57 offset0:16 offset1:17
	ds_write2_b32 v220, v58, v59 offset0:18 offset1:19
	ds_write2_b32 v220, v60, v61 offset0:24 offset1:25
	ds_write2_b32 v220, v62, v63 offset0:26 offset1:27
	s_nop 3
	ds_write2_b32 v237, v32, v33 offset1:1
	ds_write2_b32 v238, v34, v35 offset1:1
	ds_write2_b32 v239, v36, v37 offset1:1
	ds_write2_b32 v240, v38, v39 offset1:1
	ds_write2_b32 v241, v40, v41 offset1:1
	ds_write2_b32 v242, v42, v43 offset1:1
	ds_write2_b32 v243, v44, v45 offset1:1
	ds_write2_b32 v244, v46, v47 offset1:1
	ds_read_b64_tr_b16 v[32:33], v230 offset:33280
	ds_read_b64_tr_b16 v[34:35], v230 offset:35584
	ds_read_b64_tr_b16 v[36:37], v230 offset:42496
	ds_read_b64_tr_b16 v[38:39], v230 offset:44800
	ds_read_b64_tr_b16 v[40:41], v230 offset:51712
	ds_read_b64_tr_b16 v[42:43], v230 offset:54016
	ds_read_b64_tr_b16 v[44:45], v230 offset:60928
	ds_read_b64_tr_b16 v[46:47], v230 offset:63232
	ds_read_b64_tr_b16 v[48:49], v230 offset:33344
	ds_read_b64_tr_b16 v[50:51], v230 offset:35648
	ds_read_b64_tr_b16 v[52:53], v230 offset:42560
	ds_read_b64_tr_b16 v[54:55], v230 offset:44864
	ds_read_b64_tr_b16 v[56:57], v230 offset:51776
	ds_read_b64_tr_b16 v[58:59], v230 offset:54080
	ds_read_b64_tr_b16 v[60:61], v230 offset:60992
	ds_read_b64_tr_b16 v[62:63], v230 offset:63296
	s_waitcnt lgkmcnt(14)
	v_mfma_f32_32x32x16_bf16 v[16:31], v[32:35], v[110:113], v[16:31]
	s_waitcnt lgkmcnt(12)
	v_mfma_f32_32x32x16_bf16 v[16:31], v[36:39], v[114:117], v[16:31]
	s_waitcnt lgkmcnt(10)
	v_mfma_f32_32x32x16_bf16 v[16:31], v[40:43], v[118:121], v[16:31]
	s_waitcnt lgkmcnt(8)
	v_mfma_f32_32x32x16_bf16 v[16:31], v[44:47], v[246:249], v[16:31]
	s_waitcnt lgkmcnt(6)
	v_mfma_f32_32x32x16_bf16 v[0:15], v[48:51], v[110:113], v[0:15]
	s_waitcnt lgkmcnt(4)
	v_mfma_f32_32x32x16_bf16 v[0:15], v[52:55], v[114:117], v[0:15]
	s_waitcnt lgkmcnt(2)
	v_mfma_f32_32x32x16_bf16 v[0:15], v[56:59], v[118:121], v[0:15]
	s_waitcnt lgkmcnt(0)
	s_barrier
	s_waitcnt vmcnt(11)
	ds_write2_b64 v146, v[64:65], v[66:67] offset1:1
	s_waitcnt vmcnt(10)
	ds_write_b128 v231, v[68:71] offset:33280
	s_waitcnt vmcnt(9)
	ds_write2_b64 v147, v[72:73], v[74:75] offset1:1
	s_waitcnt vmcnt(8)
	ds_write_b128 v231, v[76:79] offset:42496
	s_waitcnt vmcnt(7)
	ds_write2_b64 v245, v[88:89], v[90:91] offset1:1
	s_waitcnt vmcnt(6)
	ds_write_b128 v231, v[92:95] offset:51712
	s_waitcnt vmcnt(5)
	ds_write2_b64 v108, v[96:97], v[98:99] offset1:1
	s_waitcnt vmcnt(4)
	ds_write_b128 v231, v[100:103] offset:60928
	s_waitcnt vmcnt(3)
	ds_write_b128 v234, v[104:107]
	v_mfma_f32_32x32x16_bf16 v[0:15], v[60:63], v[246:249], v[0:15]
	v_lshl_add_u64 v[32:33], v[170:171], 0, s[4:5]
	v_add_co_u32_e32 v34, vcc, s21, v32
	global_load_dwordx4 v[88:91], v[32:33], off
	global_load_dwordx4 v[92:95], v[32:33], off offset:2048
	v_addc_co_u32_e32 v35, vcc, 0, v33, vcc
	global_load_dwordx4 v[96:99], v[34:35], off
	global_load_dwordx4 v[100:103], v[34:35], off offset:2048
	v_add_co_u32_e32 v34, vcc, s24, v32
	s_nop 1
	v_addc_co_u32_e32 v35, vcc, 0, v33, vcc
	v_add_co_u32_e32 v32, vcc, s25, v32
	global_load_dwordx4 v[104:107], v[34:35], off
	global_load_dwordx4 v[108:111], v[34:35], off offset:2048
	v_addc_co_u32_e32 v33, vcc, 0, v33, vcc
	global_load_dwordx4 v[112:115], v[32:33], off
	global_load_dwordx4 v[116:119], v[32:33], off offset:2048
	v_lshl_add_u64 v[32:33], v[176:177], 0, s[4:5]
	global_load_dwordx4 v[120:123], v[32:33], off
	s_waitcnt lgkmcnt(3)
	ds_read2_b32 v[32:33], v223 offset1:1
	ds_read2_b32 v[34:35], v134 offset1:1
	ds_read2_b32 v[36:37], v135 offset1:1
	ds_read2_b32 v[38:39], v136 offset1:1
	ds_read2_b32 v[40:41], v224 offset1:1
	ds_read2_b32 v[42:43], v137 offset1:1
	ds_read2_b32 v[44:45], v138 offset1:1
	ds_read2_b32 v[46:47], v139 offset1:1
	s_waitcnt lgkmcnt(4)
	ds_read2_b32 v[48:49], v225 offset1:1
	ds_read2_b32 v[50:51], v140 offset1:1
	ds_read2_b32 v[52:53], v141 offset1:1
	ds_read2_b32 v[54:55], v142 offset1:1
	v_add_f32_e32 v32, 0, v32
	v_add_f32_e32 v33, 0, v33
	s_nop 0
	v_add_f32_e32 v32, v32, v34
	v_add_f32_e32 v33, v33, v35
	s_nop 0
	v_add_f32_e32 v32, v32, v36
	v_add_f32_e32 v33, v33, v37
	s_nop 0
	v_add_f32_e32 v32, v32, v38
	v_add_f32_e32 v33, v33, v39
	s_nop 0
	v_cvt_pk_bf16_f32 v32, v32, v33
	s_waitcnt lgkmcnt(4)
	ds_read2_b32 v[56:57], v226 offset1:1
	ds_read2_b32 v[58:59], v143 offset1:1
	ds_read2_b32 v[60:61], v144 offset1:1
	ds_read2_b32 v[62:63], v145 offset1:1
	v_add_f32_e32 v40, 0, v40
	v_add_f32_e32 v41, 0, v41
	s_nop 0
	v_add_f32_e32 v40, v40, v42
	v_add_f32_e32 v41, v41, v43
	s_nop 0
	v_add_f32_e32 v40, v40, v44
	v_add_f32_e32 v41, v41, v45
	s_nop 0
	v_add_f32_e32 v40, v40, v46
	v_add_f32_e32 v41, v41, v47
	s_nop 0
	v_cvt_pk_bf16_f32 v33, v40, v41
	v_add_co_u32_e32 v36, vcc, s40, v132
	s_nop 1
	v_addc_co_u32_e32 v37, vcc, 0, v133, vcc
	s_waitcnt lgkmcnt(4)
	v_add_f32_e32 v48, 0, v48
	v_add_f32_e32 v49, 0, v49
	s_nop 0
	v_add_f32_e32 v48, v48, v50
	v_add_f32_e32 v49, v49, v51
	s_nop 0
	v_add_f32_e32 v48, v48, v52
	v_add_f32_e32 v49, v49, v53
	s_nop 0
	v_add_f32_e32 v48, v48, v54
	v_add_f32_e32 v49, v49, v55
	s_nop 0
	v_cvt_pk_bf16_f32 v34, v48, v49
	s_waitcnt lgkmcnt(0)
	v_add_f32_e32 v56, 0, v56
	v_add_f32_e32 v57, 0, v57
	s_nop 0
	v_add_f32_e32 v56, v56, v58
	v_add_f32_e32 v57, v57, v59
	s_nop 0
	v_add_f32_e32 v56, v56, v60
	v_add_f32_e32 v57, v57, v61
	s_nop 0
	v_add_f32_e32 v56, v56, v62
	v_add_f32_e32 v57, v57, v63
	s_nop 0
	v_cvt_pk_bf16_f32 v35, v56, v57
	global_store_dwordx4 v[36:37], v[32:35], off
	s_barrier
	s_cbranch_scc0 .LBB0_363
	s_cmpk_lt_u32 s41, 0x80
	s_cbranch_scc0 .LBB0_361
	v_lshl_or_b32 v32, s42, 9, v156
	v_or_b32_e32 v32, s43, v32
	v_lshlrev_b32_e32 v32, 9, v32
	v_mov_b32_e32 v33, v151
	v_lshl_add_u64 v[32:33], v[158:159], 0, v[32:33]
	v_cvt_pk_bf16_f32 v16, v16, v17
	v_cvt_pk_bf16_f32 v17, v18, v19
	v_cvt_pk_bf16_f32 v0, v0, v1
	v_cvt_pk_bf16_f32 v1, v2, v3
	global_store_dwordx2 v[32:33], v[16:17], off
	v_cvt_pk_bf16_f32 v16, v20, v21
	v_cvt_pk_bf16_f32 v17, v22, v23
	global_store_dwordx2 v[32:33], v[0:1], off offset:64
	v_cvt_pk_bf16_f32 v0, v4, v5
	v_cvt_pk_bf16_f32 v1, v6, v7
	global_store_dwordx2 v[32:33], v[16:17], off offset:16
	v_cvt_pk_bf16_f32 v16, v24, v25
	v_cvt_pk_bf16_f32 v17, v26, v27
	global_store_dwordx2 v[32:33], v[0:1], off offset:80
	v_cvt_pk_bf16_f32 v0, v8, v9
	v_cvt_pk_bf16_f32 v1, v10, v11
	global_store_dwordx2 v[32:33], v[16:17], off offset:32
	v_cvt_pk_bf16_f32 v16, v28, v29
	v_cvt_pk_bf16_f32 v17, v30, v31
	global_store_dwordx2 v[32:33], v[0:1], off offset:96
	v_cvt_pk_bf16_f32 v0, v12, v13
	v_cvt_pk_bf16_f32 v1, v14, v15
	global_store_dwordx2 v[32:33], v[16:17], off offset:48
	global_store_dwordx2 v[32:33], v[0:1], off offset:112
	s_branch .LBB0_361
